# non-temporal (nt) hint on the prepass loads of the read-once f32 inputs (x, raw weights): they no longer displace the bf16 copies / GEMM operands from the caches
# speedup vs baseline: 1.0362x; 1.0362x over previous
.LBB0_481:
	s_mul_hi_i32 s2, s22, 0x84210843
	s_add_i32 s2, s2, s22
	s_lshr_b32 s3, s2, 31
	s_ashr_i32 s2, s2, 8
	s_add_i32 s4, s2, s3
	s_mul_i32 s2, s4, 0xfffffe10
	s_add_i32 s8, s22, s2
	s_cmpk_gt_i32 s8, 0x17f
	s_cbranch_scc0 .LBB0_492
	s_cmpk_gt_u32 s8, 0x1af
	s_cbranch_scc0 .LBB0_493
	s_ashr_i32 s5, s4, 31
	s_lshl_b64 s[2:3], s[4:5], 22
	v_readlane_b32 s24, v254, 1
	v_readlane_b32 s25, v254, 2
	s_add_u32 s2, s24, s2
	s_mul_i32 s6, s4, 0xffffe100
	s_addc_u32 s3, s25, s3
	s_add_i32 s6, s20, s6
	v_mov_b32_e32 v35, v206
	s_and_b32 s7, s12, 0x3c0
	s_and_b32 s6, s6, 0x7fffff00
	s_addk_i32 s6, 0xe500
	v_lshlrev_b32_e32 v0, 2, v35
	v_ashrrev_i32_e32 v32, 6, v35
	v_add_u32_e32 v6, 0x200, v35
	v_and_b32_e32 v7, 0xfc, v0
	v_add_u32_e32 v2, s7, v32
	v_ashrrev_i32_e32 v33, 6, v6
	v_or_b32_e32 v176, s6, v7
	v_ashrrev_i32_e32 v3, 31, v2
	v_add_u32_e32 v4, s7, v33
	v_lshl_add_u64 v[0:1], v[176:177], 2, s[2:3]
	v_lshlrev_b64 v[2:3], 12, v[2:3]
	v_ashrrev_i32_e32 v5, 31, v4
	v_lshl_add_u64 v[2:3], v[0:1], 0, v[2:3]
	v_lshlrev_b64 v[4:5], 12, v[4:5]
	s_waitcnt vmcnt(0)
	s_barrier
	v_lshl_add_u64 v[4:5], v[0:1], 0, v[4:5]
	global_load_dwordx4 v[8:11], v[2:3], off nt
	global_load_dwordx4 v[12:15], v[4:5], off nt
	v_add_u32_e32 v3, 0x400, v35
	v_add_u32_e32 v2, 0x600, v35
	v_ashrrev_i32_e32 v44, 6, v3
	v_ashrrev_i32_e32 v46, 6, v2
	v_add_u32_e32 v4, s7, v44
	v_add_u32_e32 v16, s7, v46
	v_ashrrev_i32_e32 v5, 31, v4
	v_ashrrev_i32_e32 v17, 31, v16
	v_lshlrev_b64 v[4:5], 12, v[4:5]
	v_lshlrev_b64 v[16:17], 12, v[16:17]
	v_lshl_add_u64 v[4:5], v[0:1], 0, v[4:5]
	v_lshl_add_u64 v[20:21], v[0:1], 0, v[16:17]
	global_load_dwordx4 v[16:19], v[4:5], off nt
	s_nop 0
	global_load_dwordx4 v[20:23], v[20:21], off nt
	v_add_u32_e32 v4, 0x800, v35
	v_add_u32_e32 v24, 0xa00, v35
	v_ashrrev_i32_e32 v47, 6, v4
	v_ashrrev_i32_e32 v48, 6, v24
	v_add_u32_e32 v4, s7, v47
	v_add_u32_e32 v24, s7, v48
	v_ashrrev_i32_e32 v5, 31, v4
	v_ashrrev_i32_e32 v25, 31, v24
	v_lshlrev_b64 v[4:5], 12, v[4:5]
	v_lshlrev_b64 v[24:25], 12, v[24:25]
	v_lshl_add_u64 v[4:5], v[0:1], 0, v[4:5]
	v_lshl_add_u64 v[28:29], v[0:1], 0, v[24:25]
	global_load_dwordx4 v[24:27], v[4:5], off nt
	s_nop 0
	global_load_dwordx4 v[28:31], v[28:29], off nt
	v_add_u32_e32 v4, 0xc00, v35
	v_ashrrev_i32_e32 v49, 6, v4
	v_add_u32_e32 v4, s7, v49
	v_ashrrev_i32_e32 v5, 31, v4
	v_lshlrev_b64 v[4:5], 12, v[4:5]
	v_lshl_add_u64 v[4:5], v[0:1], 0, v[4:5]
	global_load_dwordx4 v[36:39], v[4:5], off nt
	v_add_u32_e32 v4, 0xe00, v35
	v_ashrrev_i32_e32 v50, 6, v4
	v_add_u32_e32 v4, s7, v50
	v_ashrrev_i32_e32 v5, 31, v4
	v_lshlrev_b64 v[4:5], 12, v[4:5]
	v_lshl_add_u64 v[0:1], v[0:1], 0, v[4:5]
	global_load_dwordx4 v[40:43], v[0:1], off nt
	s_lshl_b64 s[2:3], s[4:5], 21
	v_lshlrev_b32_e32 v0, 2, v7
	v_mad_u64_u32 v[4:5], s[24:25], v32, s15, v[0:1]
	s_add_u32 s5, s43, s2
	v_readlane_b32 s2, v254, 23
	v_mad_u64_u32 v[32:33], s[24:25], v33, s15, v[0:1]
	v_mad_u64_u32 v[44:45], s[24:25], v44, s15, v[0:1]
	s_addc_u32 s9, s2, s3
	v_readlane_b32 s26, v254, 3
	v_readlane_b32 s27, v254, 4
	v_readlane_b32 s28, v254, 5
	v_readlane_b32 s29, v254, 6
	v_readlane_b32 s30, v254, 7
	v_readlane_b32 s31, v254, 8
	s_waitcnt vmcnt(7)
	ds_write2_b32 v4, v8, v9 offset1:1
	ds_write2_b32 v4, v10, v11 offset0:2 offset1:3
	s_waitcnt vmcnt(6)
	ds_write2_b32 v32, v12, v13 offset1:1
	ds_write2_b32 v32, v14, v15 offset0:2 offset1:3
	s_waitcnt vmcnt(5)
	ds_write2_b32 v44, v16, v17 offset1:1
	ds_write2_b32 v44, v18, v19 offset0:2 offset1:3
	v_mad_u64_u32 v[4:5], s[2:3], v46, s15, v[0:1]
	s_waitcnt vmcnt(4)
	ds_write2_b32 v4, v20, v21 offset1:1
	ds_write2_b32 v4, v22, v23 offset0:2 offset1:3
	v_mad_u64_u32 v[4:5], s[2:3], v47, s15, v[0:1]
	s_waitcnt vmcnt(3)
	ds_write2_b32 v4, v24, v25 offset1:1
	ds_write2_b32 v4, v26, v27 offset0:2 offset1:3
	v_mad_u64_u32 v[4:5], s[2:3], v48, s15, v[0:1]
	s_waitcnt vmcnt(2)
	ds_write2_b32 v4, v28, v29 offset1:1
	ds_write2_b32 v4, v30, v31 offset0:2 offset1:3
	v_mad_u64_u32 v[4:5], s[2:3], v49, s15, v[0:1]
	v_mad_u64_u32 v[0:1], s[2:3], v50, s15, v[0:1]
	s_waitcnt vmcnt(1)
	ds_write2_b32 v4, v36, v37 offset1:1
	ds_write2_b32 v4, v38, v39 offset0:2 offset1:3
	s_waitcnt vmcnt(0)
	ds_write2_b32 v0, v40, v41 offset1:1
	ds_write2_b32 v0, v42, v43 offset0:2 offset1:3
	v_lshlrev_b32_e32 v0, 3, v35
	s_lshl_b32 s2, s7, 1
	v_and_b32_e32 v0, 56, v0
	s_add_u32 s2, s5, s2
	v_ashrrev_i32_e32 v1, 3, v35
	v_mul_u32_u24_e32 v7, 0x404, v0
	s_addc_u32 s3, s9, 0
	v_lshlrev_b32_e32 v176, 1, v0
	v_add_u32_e32 v0, s6, v1
	v_lshl_add_u64 v[4:5], s[2:3], 0, v[176:177]
	v_cmp_gt_i32_e32 vcc, s93, v0
	s_waitcnt lgkmcnt(0)
	s_barrier
	s_and_saveexec_b64 s[2:3], vcc
	s_cbranch_execz .LBB0_485
	v_lshl_add_u32 v1, v1, 2, v7
	ds_read_b32 v8, v1
	ds_read_b32 v9, v1 offset:1028
	s_waitcnt lgkmcnt(0)
	v_cvt_pk_bf16_f32 v8, v8, v9
	ds_read_b32 v9, v1 offset:2056
	ds_read_b32 v10, v1 offset:3084
	s_waitcnt lgkmcnt(0)
	v_cvt_pk_bf16_f32 v9, v9, v10
	ds_read_b32 v10, v1 offset:4112
	ds_read_b32 v11, v1 offset:5140
	s_waitcnt lgkmcnt(0)
	v_cvt_pk_bf16_f32 v10, v10, v11
	ds_read_b32 v11, v1 offset:6168
	ds_read_b32 v1, v1 offset:7196
	s_waitcnt lgkmcnt(0)
	v_cvt_pk_bf16_f32 v11, v11, v1
	v_ashrrev_i32_e32 v1, 31, v0
	v_lshlrev_b64 v[0:1], 11, v[0:1]
	v_lshl_add_u64 v[0:1], v[4:5], 0, v[0:1]
	global_store_dwordx4 v[0:1], v[8:11], off sc1

.LBB0_494:
	s_add_i32 s2, s8, 0xfffffe80
	s_lshr_b32 s72, s2, 4
	s_mul_i32 s2, s4, 3
	s_mul_hi_i32 s3, s4, 3
	s_add_u32 s2, s2, s72
	s_addc_u32 s3, s3, 0
	s_lshl_b64 s[2:3], s[2:3], 20
	s_add_u32 s2, s58, s2
	s_mul_i32 s5, s4, 0xffff8400
	v_mov_b32_e32 v35, v206
	s_addc_u32 s3, s59, s3
	s_add_i32 s5, s12, s5
	s_and_b32 s6, s5, 0xc0
	v_lshlrev_b32_e32 v0, 2, v35
	s_and_b32 s5, s5, 0x300
	v_and_b32_e32 v7, 0xfc, v0
	v_ashrrev_i32_e32 v32, 6, v35
	v_add_u32_e32 v6, 0x200, v35
	v_or_b32_e32 v0, s5, v7
	v_add_u32_e32 v2, s6, v32
	v_ashrrev_i32_e32 v33, 6, v6
	v_lshlrev_b32_e32 v176, 2, v0
	v_ashrrev_i32_e32 v3, 31, v2
	v_add_u32_e32 v4, s6, v33
	v_lshl_add_u64 v[0:1], s[2:3], 0, v[176:177]
	v_lshlrev_b64 v[2:3], 12, v[2:3]
	v_ashrrev_i32_e32 v5, 31, v4
	v_lshl_add_u64 v[2:3], v[0:1], 0, v[2:3]
	v_lshlrev_b64 v[4:5], 12, v[4:5]
	s_waitcnt vmcnt(0)
	s_barrier
	v_lshl_add_u64 v[4:5], v[0:1], 0, v[4:5]
	global_load_dwordx4 v[8:11], v[2:3], off nt
	global_load_dwordx4 v[12:15], v[4:5], off nt
	v_add_u32_e32 v3, 0x400, v35
	v_add_u32_e32 v2, 0x600, v35
	v_ashrrev_i32_e32 v44, 6, v3
	v_ashrrev_i32_e32 v45, 6, v2
	v_add_u32_e32 v4, s6, v44
	v_add_u32_e32 v16, s6, v45
	v_ashrrev_i32_e32 v5, 31, v4
	v_ashrrev_i32_e32 v17, 31, v16
	v_lshlrev_b64 v[4:5], 12, v[4:5]
	v_lshlrev_b64 v[16:17], 12, v[16:17]
	v_lshl_add_u64 v[4:5], v[0:1], 0, v[4:5]
	v_lshl_add_u64 v[20:21], v[0:1], 0, v[16:17]
	global_load_dwordx4 v[16:19], v[4:5], off nt
	s_nop 0
	global_load_dwordx4 v[20:23], v[20:21], off nt
	v_add_u32_e32 v4, 0x800, v35
	v_add_u32_e32 v24, 0xa00, v35
	v_ashrrev_i32_e32 v46, 6, v4
	v_ashrrev_i32_e32 v47, 6, v24
	v_add_u32_e32 v4, s6, v46
	v_add_u32_e32 v24, s6, v47
	v_ashrrev_i32_e32 v5, 31, v4
	v_ashrrev_i32_e32 v25, 31, v24
	v_lshlrev_b64 v[4:5], 12, v[4:5]
	v_lshlrev_b64 v[24:25], 12, v[24:25]
	v_lshl_add_u64 v[4:5], v[0:1], 0, v[4:5]
	v_lshl_add_u64 v[28:29], v[0:1], 0, v[24:25]
	global_load_dwordx4 v[24:27], v[4:5], off nt
	s_nop 0
	global_load_dwordx4 v[28:31], v[28:29], off nt
	v_add_u32_e32 v4, 0xc00, v35
	v_ashrrev_i32_e32 v48, 6, v4
	v_add_u32_e32 v4, s6, v48
	v_ashrrev_i32_e32 v5, 31, v4
	v_lshlrev_b64 v[4:5], 12, v[4:5]
	v_lshl_add_u64 v[4:5], v[0:1], 0, v[4:5]
	global_load_dwordx4 v[36:39], v[4:5], off nt
	v_add_u32_e32 v4, 0xe00, v35
	v_ashrrev_i32_e32 v49, 6, v4
	v_add_u32_e32 v4, s6, v49
	v_ashrrev_i32_e32 v5, 31, v4
	v_lshlrev_b64 v[4:5], 12, v[4:5]
	v_lshl_add_u64 v[0:1], v[0:1], 0, v[4:5]
	global_load_dwordx4 v[40:43], v[0:1], off nt
	s_mul_i32 s9, s4, 0x180000
	v_lshlrev_b32_e32 v0, 2, v7
	s_mul_hi_i32 s7, s4, 0x180000
	v_mad_u64_u32 v[4:5], s[2:3], v32, s15, v[0:1]
	v_mad_u64_u32 v[32:33], s[2:3], v33, s15, v[0:1]
	s_add_u32 s9, s35, s9
	s_addc_u32 s7, s42, s7
	s_lshl_b64 s[2:3], s[72:73], 19
	s_add_u32 s9, s9, s2
	s_addc_u32 s7, s7, s3
	s_waitcnt vmcnt(7)
	ds_write2_b32 v4, v8, v9 offset1:1
	ds_write2_b32 v4, v10, v11 offset0:2 offset1:3
	s_waitcnt vmcnt(6)
	ds_write2_b32 v32, v12, v13 offset1:1
	ds_write2_b32 v32, v14, v15 offset0:2 offset1:3
	v_mad_u64_u32 v[4:5], s[2:3], v44, s15, v[0:1]
	s_waitcnt vmcnt(5)
	ds_write2_b32 v4, v16, v17 offset1:1
	ds_write2_b32 v4, v18, v19 offset0:2 offset1:3
	v_mad_u64_u32 v[4:5], s[2:3], v45, s15, v[0:1]
	s_waitcnt vmcnt(4)
	ds_write2_b32 v4, v20, v21 offset1:1
	ds_write2_b32 v4, v22, v23 offset0:2 offset1:3
	v_mad_u64_u32 v[4:5], s[2:3], v46, s15, v[0:1]
	s_waitcnt vmcnt(3)
	ds_write2_b32 v4, v24, v25 offset1:1
	ds_write2_b32 v4, v26, v27 offset0:2 offset1:3
	v_mad_u64_u32 v[4:5], s[2:3], v47, s15, v[0:1]
	s_waitcnt vmcnt(2)
	ds_write2_b32 v4, v28, v29 offset1:1
	ds_write2_b32 v4, v30, v31 offset0:2 offset1:3
	v_mad_u64_u32 v[4:5], s[2:3], v48, s15, v[0:1]
	v_mad_u64_u32 v[0:1], s[2:3], v49, s15, v[0:1]
	s_waitcnt vmcnt(1)
	ds_write2_b32 v4, v36, v37 offset1:1
	ds_write2_b32 v4, v38, v39 offset0:2 offset1:3
	s_waitcnt vmcnt(0)
	ds_write2_b32 v0, v40, v41 offset1:1
	ds_write2_b32 v0, v42, v43 offset0:2 offset1:3
	v_lshlrev_b32_e32 v0, 3, v35
	s_lshl_b32 s2, s6, 1
	v_and_b32_e32 v0, 56, v0
	s_add_u32 s2, s9, s2
	v_ashrrev_i32_e32 v1, 3, v35
	v_mul_u32_u24_e32 v7, 0x404, v0
	s_addc_u32 s3, s7, 0
	v_lshlrev_b32_e32 v176, 1, v0
	v_add_u32_e32 v0, s5, v1
	v_lshl_add_u64 v[4:5], s[2:3], 0, v[176:177]
	v_cmp_gt_i32_e32 vcc, s93, v0
	s_waitcnt lgkmcnt(0)
	s_barrier
	s_and_saveexec_b64 s[2:3], vcc
	s_cbranch_execz .LBB0_496
	v_lshl_add_u32 v1, v1, 2, v7
	ds_read_b32 v8, v1
	ds_read_b32 v9, v1 offset:1028
	s_waitcnt lgkmcnt(0)
	v_cvt_pk_bf16_f32 v8, v8, v9
	ds_read_b32 v9, v1 offset:2056
	ds_read_b32 v10, v1 offset:3084
	s_waitcnt lgkmcnt(0)
	v_cvt_pk_bf16_f32 v9, v9, v10
	ds_read_b32 v10, v1 offset:4112
	ds_read_b32 v11, v1 offset:5140
	s_waitcnt lgkmcnt(0)
	v_cvt_pk_bf16_f32 v10, v10, v11
	ds_read_b32 v11, v1 offset:6168
	ds_read_b32 v1, v1 offset:7196
	s_waitcnt lgkmcnt(0)
	v_cvt_pk_bf16_f32 v11, v11, v1
	v_ashrrev_i32_e32 v1, 31, v0
	v_lshlrev_b64 v[0:1], 9, v[0:1]
	v_lshl_add_u64 v[0:1], v[4:5], 0, v[0:1]
	global_store_dwordx4 v[0:1], v[8:11], off sc1

.LBB0_504:
	s_bfe_u32 s2, s8, 0x4001b
	s_add_i32 s2, s8, s2
	s_sext_i32_i16 s3, s2
	s_and_b32 s2, s2, 0xfff0
	s_sub_i32 s2, s8, s2
	s_mul_i32 s6, s4, 0x1710000
	s_mul_hi_i32 s5, s4, 0x1710000
	s_add_u32 s6, s46, s6
	v_mov_b32_e32 v38, v206
	s_addc_u32 s7, s47, s5
	s_lshl_b32 s3, s3, 4
	s_and_b32 s23, s3, 0xffffff00
	v_lshlrev_b32_e32 v0, 2, v38
	v_and_b32_e32 v39, 0xfc, v0
	v_or_b32_e32 v0, s23, v39
	s_sext_i32_i16 s2, s2
	v_ashrrev_i32_e32 v1, 31, v0
	s_lshl_b32 s2, s2, 6
	v_cmp_gt_i32_e32 vcc, s16, v0
	v_lshl_add_u64 v[32:33], v[0:1], 2, s[6:7]
	v_mov_b32_e32 v0, 0
	v_ashrrev_i32_e32 v40, 6, v38
	v_mov_b32_e32 v4, 0
	v_mov_b32_e32 v5, 0
	v_mov_b32_e32 v6, 0
	v_mov_b32_e32 v7, 0
	s_waitcnt vmcnt(0)
	s_barrier
	s_and_saveexec_b64 s[6:7], vcc
	s_cbranch_execz .LBB0_506
	v_add_u32_e32 v1, s2, v40
	v_mad_i64_i32 v[2:3], s[8:9], v1, s17, v[32:33]
	global_load_dwordx4 v[4:7], v[2:3], off nt
.LBB0_506:
	s_or_b64 exec, exec, s[6:7]
	v_add_u32_e32 v37, 0x200, v38
	v_ashrrev_i32_e32 v41, 6, v37
	v_mov_b32_e32 v1, 0
	v_mov_b32_e32 v2, 0
	v_mov_b32_e32 v3, 0
	s_and_saveexec_b64 s[6:7], vcc
	s_cbranch_execz .LBB0_508
	v_add_u32_e32 v0, s2, v41
	v_mad_i64_i32 v[0:1], s[8:9], v0, s17, v[32:33]
	global_load_dwordx4 v[0:3], v[0:1], off nt
.LBB0_508:
	s_or_b64 exec, exec, s[6:7]
	v_add_u32_e32 v36, 0x400, v38
	v_mov_b32_e32 v8, 0
	v_ashrrev_i32_e32 v42, 6, v36
	v_mov_b32_e32 v12, 0
	v_mov_b32_e32 v13, 0
	v_mov_b32_e32 v14, 0
	v_mov_b32_e32 v15, 0
	s_and_saveexec_b64 s[6:7], vcc
	s_cbranch_execz .LBB0_510
	v_add_u32_e32 v9, s2, v42
	v_mad_i64_i32 v[10:11], s[8:9], v9, s17, v[32:33]
	global_load_dwordx4 v[12:15], v[10:11], off nt
.LBB0_510:
	s_or_b64 exec, exec, s[6:7]
	v_add_u32_e32 v35, 0x600, v38
	v_ashrrev_i32_e32 v43, 6, v35
	v_mov_b32_e32 v9, 0
	v_mov_b32_e32 v10, 0
	v_mov_b32_e32 v11, 0
	s_and_saveexec_b64 s[6:7], vcc
	s_cbranch_execz .LBB0_512
	v_add_u32_e32 v8, s2, v43
	v_mad_i64_i32 v[8:9], s[8:9], v8, s17, v[32:33]
	global_load_dwordx4 v[8:11], v[8:9], off nt
.LBB0_512:
	s_or_b64 exec, exec, s[6:7]
	v_add_u32_e32 v17, 0x800, v38
	v_mov_b32_e32 v16, 0
	v_ashrrev_i32_e32 v44, 6, v17
	v_mov_b32_e32 v20, 0
	v_mov_b32_e32 v21, 0
	v_mov_b32_e32 v22, 0
	v_mov_b32_e32 v23, 0
	s_and_saveexec_b64 s[6:7], vcc
	s_cbranch_execz .LBB0_514
	v_add_u32_e32 v17, s2, v44
	v_mad_i64_i32 v[18:19], s[8:9], v17, s17, v[32:33]
	global_load_dwordx4 v[20:23], v[18:19], off nt
.LBB0_514:
	s_or_b64 exec, exec, s[6:7]
	v_add_u32_e32 v17, 0xa00, v38
	v_ashrrev_i32_e32 v45, 6, v17
	v_mov_b32_e32 v17, 0
	v_mov_b32_e32 v18, 0
	v_mov_b32_e32 v19, 0
	s_and_saveexec_b64 s[6:7], vcc
	s_cbranch_execz .LBB0_516
	v_add_u32_e32 v16, s2, v45
	v_mad_i64_i32 v[16:17], s[8:9], v16, s17, v[32:33]
	global_load_dwordx4 v[16:19], v[16:17], off nt
.LBB0_516:
	s_or_b64 exec, exec, s[6:7]
	v_add_u32_e32 v25, 0xc00, v38
	v_mov_b32_e32 v24, 0
	v_ashrrev_i32_e32 v46, 6, v25
	v_mov_b32_e32 v28, 0
	v_mov_b32_e32 v29, 0
	v_mov_b32_e32 v30, 0
	v_mov_b32_e32 v31, 0
	s_and_saveexec_b64 s[6:7], vcc
	s_cbranch_execz .LBB0_518
	v_add_u32_e32 v25, s2, v46
	v_mad_i64_i32 v[26:27], s[8:9], v25, s17, v[32:33]
	global_load_dwordx4 v[28:31], v[26:27], off nt
.LBB0_518:
	s_or_b64 exec, exec, s[6:7]
	v_add_u32_e32 v25, 0xe00, v38
	v_ashrrev_i32_e32 v47, 6, v25
	v_mov_b32_e32 v25, 0
	v_mov_b32_e32 v26, 0
	v_mov_b32_e32 v27, 0
	s_and_saveexec_b64 s[6:7], vcc
	s_cbranch_execz .LBB0_520
	v_add_u32_e32 v24, s2, v47
	v_mad_i64_i32 v[24:25], s[8:9], v24, s17, v[32:33]
	global_load_dwordx4 v[24:27], v[24:25], off nt

.LBB0_574:
	v_add_u32_e32 v18, s8, v0
	v_ashrrev_i32_e32 v1, 31, v0
	v_ashrrev_i32_e32 v19, 31, v18
	v_lshl_add_u64 v[6:7], v[0:1], 4, s[44:45]
	v_lshl_add_u64 v[10:11], v[18:19], 4, s[44:45]
	global_load_dwordx4 v[2:5], v[6:7], off nt
	v_add_u32_e32 v20, s10, v0
	global_load_dwordx4 v[10:13], v[10:11], off nt
	v_lshl_add_u64 v[6:7], s[2:3], 4, v[6:7]
	global_load_dwordx4 v[6:9], v[6:7], off nt
	v_ashrrev_i32_e32 v21, 31, v20
	v_lshl_add_u64 v[14:15], v[20:21], 4, s[44:45]
	global_load_dwordx4 v[14:17], v[14:15], off nt
	v_lshl_add_u64 v[0:1], v[0:1], 3, s[80:81]
	s_waitcnt vmcnt(0)
	v_cvt_pk_bf16_f32 v2, v2, v3
	v_cvt_pk_bf16_f32 v3, v4, v5
	global_store_dwordx2 v[0:1], v[2:3], off
	v_lshl_add_u64 v[0:1], s[2:3], 3, v[0:1]
	v_cvt_pk_bf16_f32 v2, v6, v7
	v_cvt_pk_bf16_f32 v3, v8, v9
	global_store_dwordx2 v[0:1], v[2:3], off
	v_cvt_pk_bf16_f32 v0, v10, v11
	v_cvt_pk_bf16_f32 v1, v12, v13
	v_lshl_add_u64 v[2:3], v[18:19], 3, s[80:81]
	global_store_dwordx2 v[2:3], v[0:1], off
	v_cvt_pk_bf16_f32 v0, v14, v15
	v_cvt_pk_bf16_f32 v1, v16, v17
	v_lshl_add_u64 v[2:3], v[20:21], 3, s[80:81]
	global_store_dwordx2 v[2:3], v[0:1], off
	v_add_u32_e32 v0, s8, v18
	v_add_u32_e32 v1, s10, v0
	v_cmp_lt_i32_e32 vcc, s18, v1
	s_or_b64 s[6:7], vcc, s[6:7]
	s_andn2_b64 exec, exec, s[6:7]
	s_cbranch_execnz .LBB0_574
	s_or_b64 exec, exec, s[6:7]

.LBB0_578:
	global_load_dwordx4 v[6:9], v[2:3], off nt
	v_add_u32_e32 v0, s2, v0
	v_cmp_lt_i32_e32 vcc, s18, v0
	v_lshl_add_u64 v[2:3], v[2:3], 0, s[6:7]
	s_or_b64 s[10:11], vcc, s[10:11]
	s_waitcnt vmcnt(0)
	v_cvt_pk_bf16_f32 v6, v6, v7
	v_cvt_pk_bf16_f32 v7, v8, v9
	global_store_dwordx2 v[4:5], v[6:7], off
	v_lshl_add_u64 v[4:5], v[4:5], 0, s[8:9]
	s_andn2_b64 exec, exec, s[10:11]
	s_cbranch_execnz .LBB0_578
